# v32 + merge epilogues hand-rewritten + P1 zeroing peeled + deferred scan counter update
# speedup vs baseline: 1.0101x; 1.0101x over previous
.LBB0_187:
	s_add_u32 s14, s4, 0x100
	s_addc_u32 s15, s5, 0
	s_mov_b32 s16, -2
	ds_read_b128 v[128:131], v168
	ds_read_b128 v[152:155], v168 offset:1024
	ds_read_b128 v[180:183], v168 offset:2048
	ds_read_b128 v[184:187], v168 offset:3072
	ds_read_b128 v[188:191], v169
	ds_read_b128 v[192:195], v169 offset:1024
	ds_read_b128 v[196:199], v169 offset:2048
	ds_read_b128 v[200:203], v169 offset:3072
	s_add_u32 s4, s0, 0x100
	s_addc_u32 s5, s1, 0
	s_cmp_eq_u32 s16, 12
	s_cselect_b32 s13, s95, s5
	s_cselect_b32 s12, s94, s4
	s_cselect_b32 s11, s97, s15
	s_cselect_b32 s10, s96, s14
	v_lshl_add_u64 v[156:157], s[0:1], 0, v[144:145]
	s_add_i32 m0, s89, 0xc000
	ds_read_b128 v[204:207], v170
	ds_read_b128 v[208:211], v170 offset:1024
	ds_read_b128 v[212:215], v170 offset:2048
	ds_read_b128 v[216:219], v170 offset:3072
	ds_read_b128 v[220:223], v170 offset:4096
	ds_read_b128 v[224:227], v170 offset:5120
	ds_read_b128 v[228:231], v170 offset:6144
	ds_read_b128 v[232:235], v170 offset:7168
	global_load_lds_dwordx4 v[156:157], off
	v_lshl_add_u64 v[156:157], s[0:1], 0, v[146:147]
	s_add_i32 m0, s89, 0xe000
	s_nop 0
	global_load_lds_dwordx4 v[156:157], off
	s_waitcnt vmcnt(8)
	s_waitcnt lgkmcnt(0)
	s_barrier
	s_waitcnt lgkmcnt(0)
	v_mfma_f32_16x16x32_f16 v[84:87], v[128:131], v[204:207], 0
	v_mfma_f32_16x16x32_f16 v[92:95], v[180:183], v[204:207], 0
	v_mfma_f32_16x16x32_f16 v[68:71], v[128:131], v[212:215], 0
	v_mfma_f32_16x16x32_f16 v[76:79], v[180:183], v[212:215], 0
	v_mfma_f32_16x16x32_f16 v[52:55], v[128:131], v[220:223], 0
	v_mfma_f32_16x16x32_f16 v[124:127], v[180:183], v[220:223], 0
	v_mfma_f32_16x16x32_f16 v[60:63], v[128:131], v[228:231], 0
	v_mfma_f32_16x16x32_f16 v[116:119], v[180:183], v[228:231], 0
	v_mfma_f32_16x16x32_f16 v[84:87], v[152:155], v[208:211], v[84:87]
	v_mfma_f32_16x16x32_f16 v[92:95], v[184:187], v[208:211], v[92:95]
	v_mfma_f32_16x16x32_f16 v[68:71], v[152:155], v[216:219], v[68:71]
	v_mfma_f32_16x16x32_f16 v[76:79], v[184:187], v[216:219], v[76:79]
	v_mfma_f32_16x16x32_f16 v[52:55], v[152:155], v[224:227], v[52:55]
	v_mfma_f32_16x16x32_f16 v[124:127], v[184:187], v[224:227], v[124:127]
	v_mfma_f32_16x16x32_f16 v[60:63], v[152:155], v[232:235], v[60:63]
	v_mfma_f32_16x16x32_f16 v[116:119], v[184:187], v[232:235], v[116:119]
	v_mfma_f32_16x16x32_f16 v[88:91], v[188:191], v[204:207], 0
	v_mfma_f32_16x16x32_f16 v[80:83], v[196:199], v[204:207], 0
	v_mfma_f32_16x16x32_f16 v[72:75], v[188:191], v[212:215], 0
	v_mfma_f32_16x16x32_f16 v[64:67], v[196:199], v[212:215], 0
	v_mfma_f32_16x16x32_f16 v[120:123], v[188:191], v[220:223], 0
	v_mfma_f32_16x16x32_f16 v[48:51], v[196:199], v[220:223], 0
	v_mfma_f32_16x16x32_f16 v[112:115], v[188:191], v[228:231], 0
	v_mfma_f32_16x16x32_f16 v[56:59], v[196:199], v[228:231], 0
	v_mfma_f32_16x16x32_f16 v[88:91], v[192:195], v[208:211], v[88:91]
	v_mfma_f32_16x16x32_f16 v[80:83], v[200:203], v[208:211], v[80:83]
	v_mfma_f32_16x16x32_f16 v[72:75], v[192:195], v[216:219], v[72:75]
	v_mfma_f32_16x16x32_f16 v[64:67], v[200:203], v[216:219], v[64:67]
	v_mfma_f32_16x16x32_f16 v[120:123], v[192:195], v[224:227], v[120:123]
	v_mfma_f32_16x16x32_f16 v[48:51], v[200:203], v[224:227], v[48:51]
	v_mfma_f32_16x16x32_f16 v[112:115], v[192:195], v[232:235], v[112:115]
	v_mfma_f32_16x16x32_f16 v[56:59], v[200:203], v[232:235], v[56:59]
	s_barrier
	s_add_i32 s0, s23, s88
	v_lshl_add_u64 v[156:157], s[10:11], 0, v[134:135]
	s_mov_b32 m0, s0
	ds_read_b128 v[204:207], v170 offset:16384
	ds_read_b128 v[208:211], v170 offset:17408
	ds_read_b128 v[212:215], v170 offset:18432
	ds_read_b128 v[216:219], v170 offset:19456
	ds_read_b128 v[220:223], v170 offset:20480
	ds_read_b128 v[224:227], v170 offset:21504
	ds_read_b128 v[228:231], v170 offset:22528
	ds_read_b128 v[232:235], v170 offset:23552
	global_load_lds_dwordx4 v[156:157], off
	s_add_i32 m0, s0, 0x2000
	s_add_u32 s0, s10, 0x40000
	v_lshl_add_u64 v[236:237], s[10:11], 0, v[138:139]
	s_addc_u32 s1, s11, 0
	s_add_i32 s17, s22, s88
	global_load_lds_dwordx4 v[236:237], off
	v_lshl_add_u64 v[238:239], s[0:1], 0, v[134:135]
	s_mov_b32 m0, s17
	v_lshl_add_u64 v[240:241], s[12:13], 0, v[136:137]
	global_load_lds_dwordx4 v[238:239], off
	v_lshl_add_u64 v[238:239], s[0:1], 0, v[138:139]
	s_add_i32 m0, s17, 0x2000
	s_nop 0
	global_load_lds_dwordx4 v[238:239], off
	v_lshl_add_u64 v[238:239], s[12:13], 0, v[132:133]
	s_mov_b32 m0, s89
	s_nop 0
	global_load_lds_dwordx4 v[238:239], off
	s_mov_b32 m0, s3
	s_nop 0
	global_load_lds_dwordx4 v[240:241], off
	s_waitcnt vmcnt(8)
	s_waitcnt lgkmcnt(0)
	s_barrier
	s_waitcnt lgkmcnt(0)
	v_mfma_f32_16x16x32_f16 v[36:39], v[128:131], v[204:207], 0
	v_mfma_f32_16x16x32_f16 v[44:47], v[180:183], v[204:207], 0
	v_mfma_f32_16x16x32_f16 v[20:23], v[128:131], v[212:215], 0
	v_mfma_f32_16x16x32_f16 v[32:35], v[180:183], v[212:215], 0
	v_mfma_f32_16x16x32_f16 v[4:7], v[128:131], v[220:223], 0
	v_mfma_f32_16x16x32_f16 v[108:111], v[180:183], v[220:223], 0
	v_mfma_f32_16x16x32_f16 v[12:15], v[128:131], v[228:231], 0
	v_mfma_f32_16x16x32_f16 v[100:103], v[180:183], v[228:231], 0
	v_mfma_f32_16x16x32_f16 v[36:39], v[152:155], v[208:211], v[36:39]
	v_mfma_f32_16x16x32_f16 v[44:47], v[184:187], v[208:211], v[44:47]
	v_mfma_f32_16x16x32_f16 v[20:23], v[152:155], v[216:219], v[20:23]
	v_mfma_f32_16x16x32_f16 v[32:35], v[184:187], v[216:219], v[32:35]
	v_mfma_f32_16x16x32_f16 v[4:7], v[152:155], v[224:227], v[4:7]
	v_mfma_f32_16x16x32_f16 v[108:111], v[184:187], v[224:227], v[108:111]
	v_mfma_f32_16x16x32_f16 v[12:15], v[152:155], v[232:235], v[12:15]
	v_mfma_f32_16x16x32_f16 v[100:103], v[184:187], v[232:235], v[100:103]
	v_mfma_f32_16x16x32_f16 v[40:43], v[188:191], v[204:207], 0
	v_mfma_f32_16x16x32_f16 v[28:31], v[196:199], v[204:207], 0
	v_mfma_f32_16x16x32_f16 v[24:27], v[188:191], v[212:215], 0
	v_mfma_f32_16x16x32_f16 v[16:19], v[196:199], v[212:215], 0
	v_mfma_f32_16x16x32_f16 v[104:107], v[188:191], v[220:223], 0
	v_mfma_f32_16x16x32_f16 v[0:3], v[196:199], v[220:223], 0
	v_mfma_f32_16x16x32_f16 v[96:99], v[188:191], v[228:231], 0
	v_mfma_f32_16x16x32_f16 v[8:11], v[196:199], v[228:231], 0
	v_mfma_f32_16x16x32_f16 v[40:43], v[192:195], v[208:211], v[40:43]
	v_mfma_f32_16x16x32_f16 v[28:31], v[200:203], v[208:211], v[28:31]
	v_mfma_f32_16x16x32_f16 v[24:27], v[192:195], v[216:219], v[24:27]
	v_mfma_f32_16x16x32_f16 v[16:19], v[200:203], v[216:219], v[16:19]
	v_mfma_f32_16x16x32_f16 v[104:107], v[192:195], v[224:227], v[104:107]
	v_mfma_f32_16x16x32_f16 v[0:3], v[200:203], v[224:227], v[0:3]
	v_mfma_f32_16x16x32_f16 v[96:99], v[192:195], v[232:235], v[96:99]
	v_mfma_f32_16x16x32_f16 v[8:11], v[200:203], v[232:235], v[8:11]
	s_barrier
	ds_read_b128 v[128:131], v171
	ds_read_b128 v[152:155], v171 offset:1024
	ds_read_b128 v[180:183], v171 offset:2048
	ds_read_b128 v[184:187], v171 offset:3072
	ds_read_b128 v[188:191], v172
	ds_read_b128 v[192:195], v172 offset:1024
	ds_read_b128 v[196:199], v172 offset:2048
	ds_read_b128 v[200:203], v172 offset:3072
	s_add_u32 s0, s12, 0x40000
	s_addc_u32 s1, s13, 0
	s_mov_b32 m0, s33
	v_lshl_add_u64 v[242:243], s[0:1], 0, v[132:133]
	ds_read_b128 v[204:207], v170 offset:32768
	ds_read_b128 v[208:211], v170 offset:33792
	ds_read_b128 v[212:215], v170 offset:34816
	ds_read_b128 v[216:219], v170 offset:35840
	ds_read_b128 v[220:223], v170 offset:36864
	ds_read_b128 v[224:227], v170 offset:37888
	ds_read_b128 v[228:231], v170 offset:38912
	ds_read_b128 v[232:235], v170 offset:39936
	global_load_lds_dwordx4 v[242:243], off
	v_lshl_add_u64 v[242:243], s[0:1], 0, v[136:137]
	s_mov_b32 m0, s50
	s_nop 0
	global_load_lds_dwordx4 v[242:243], off
	s_waitcnt vmcnt(8)
	s_waitcnt lgkmcnt(0)
	s_barrier
	s_waitcnt lgkmcnt(0)
	v_mfma_f32_16x16x32_f16 v[84:87], v[128:131], v[204:207], v[84:87]
	v_mfma_f32_16x16x32_f16 v[92:95], v[180:183], v[204:207], v[92:95]
	v_mfma_f32_16x16x32_f16 v[68:71], v[128:131], v[212:215], v[68:71]
	v_mfma_f32_16x16x32_f16 v[76:79], v[180:183], v[212:215], v[76:79]
	v_mfma_f32_16x16x32_f16 v[52:55], v[128:131], v[220:223], v[52:55]
	v_mfma_f32_16x16x32_f16 v[124:127], v[180:183], v[220:223], v[124:127]
	v_mfma_f32_16x16x32_f16 v[60:63], v[128:131], v[228:231], v[60:63]
	v_mfma_f32_16x16x32_f16 v[116:119], v[180:183], v[228:231], v[116:119]
	v_mfma_f32_16x16x32_f16 v[84:87], v[152:155], v[208:211], v[84:87]
	v_mfma_f32_16x16x32_f16 v[92:95], v[184:187], v[208:211], v[92:95]
	v_mfma_f32_16x16x32_f16 v[68:71], v[152:155], v[216:219], v[68:71]
	v_mfma_f32_16x16x32_f16 v[76:79], v[184:187], v[216:219], v[76:79]
	v_mfma_f32_16x16x32_f16 v[52:55], v[152:155], v[224:227], v[52:55]
	v_mfma_f32_16x16x32_f16 v[124:127], v[184:187], v[224:227], v[124:127]
	v_mfma_f32_16x16x32_f16 v[60:63], v[152:155], v[232:235], v[60:63]
	v_mfma_f32_16x16x32_f16 v[116:119], v[184:187], v[232:235], v[116:119]
	v_mfma_f32_16x16x32_f16 v[88:91], v[188:191], v[204:207], v[88:91]
	v_mfma_f32_16x16x32_f16 v[80:83], v[196:199], v[204:207], v[80:83]
	v_mfma_f32_16x16x32_f16 v[72:75], v[188:191], v[212:215], v[72:75]
	v_mfma_f32_16x16x32_f16 v[64:67], v[196:199], v[212:215], v[64:67]
	v_mfma_f32_16x16x32_f16 v[120:123], v[188:191], v[220:223], v[120:123]
	v_mfma_f32_16x16x32_f16 v[48:51], v[196:199], v[220:223], v[48:51]
	v_mfma_f32_16x16x32_f16 v[112:115], v[188:191], v[228:231], v[112:115]
	v_mfma_f32_16x16x32_f16 v[56:59], v[196:199], v[228:231], v[56:59]
	v_mfma_f32_16x16x32_f16 v[88:91], v[192:195], v[208:211], v[88:91]
	v_mfma_f32_16x16x32_f16 v[80:83], v[200:203], v[208:211], v[80:83]
	v_mfma_f32_16x16x32_f16 v[72:75], v[192:195], v[216:219], v[72:75]
	v_mfma_f32_16x16x32_f16 v[64:67], v[200:203], v[216:219], v[64:67]
	v_mfma_f32_16x16x32_f16 v[120:123], v[192:195], v[224:227], v[120:123]
	v_mfma_f32_16x16x32_f16 v[48:51], v[200:203], v[224:227], v[48:51]
	v_mfma_f32_16x16x32_f16 v[112:115], v[192:195], v[232:235], v[112:115]
	v_mfma_f32_16x16x32_f16 v[56:59], v[200:203], v[232:235], v[56:59]
	s_barrier
	s_add_i32 s0, s36, s88
	v_lshl_add_u64 v[156:157], v[156:157], 0, s[26:27]
	s_mov_b32 m0, s0
	ds_read_b128 v[204:207], v170 offset:49152
	ds_read_b128 v[208:211], v170 offset:50176
	ds_read_b128 v[212:215], v170 offset:51200
	ds_read_b128 v[216:219], v170 offset:52224
	ds_read_b128 v[220:223], v170 offset:53248
	ds_read_b128 v[224:227], v170 offset:54272
	ds_read_b128 v[228:231], v170 offset:55296
	ds_read_b128 v[232:235], v170 offset:56320
	global_load_lds_dwordx4 v[156:157], off
	s_add_i32 m0, s0, 0x2000
	s_add_u32 s0, s10, 0x40080
	v_lshl_add_u64 v[156:157], v[236:237], 0, s[26:27]
	s_addc_u32 s1, s11, 0
	s_add_i32 s10, s37, s88
	global_load_lds_dwordx4 v[156:157], off
	v_lshl_add_u64 v[156:157], s[0:1], 0, v[134:135]
	s_mov_b32 m0, s10
	s_nop 0
	global_load_lds_dwordx4 v[156:157], off
	v_lshl_add_u64 v[156:157], s[0:1], 0, v[138:139]
	s_add_i32 m0, s10, 0x2000
	s_nop 0
	global_load_lds_dwordx4 v[156:157], off
	v_lshl_add_u64 v[156:157], v[238:239], 0, s[26:27]
	s_mov_b32 m0, s51
	s_nop 0
	global_load_lds_dwordx4 v[156:157], off
	v_lshl_add_u64 v[156:157], v[240:241], 0, s[26:27]
	s_mov_b32 m0, s82
	s_nop 0
	global_load_lds_dwordx4 v[156:157], off
	s_waitcnt vmcnt(8)
	s_waitcnt lgkmcnt(0)
	s_barrier
	s_waitcnt lgkmcnt(0)
	v_mfma_f32_16x16x32_f16 v[36:39], v[128:131], v[204:207], v[36:39]
	v_mfma_f32_16x16x32_f16 v[44:47], v[180:183], v[204:207], v[44:47]
	v_mfma_f32_16x16x32_f16 v[20:23], v[128:131], v[212:215], v[20:23]
	v_mfma_f32_16x16x32_f16 v[32:35], v[180:183], v[212:215], v[32:35]
	v_mfma_f32_16x16x32_f16 v[4:7], v[128:131], v[220:223], v[4:7]
	v_mfma_f32_16x16x32_f16 v[108:111], v[180:183], v[220:223], v[108:111]
	v_mfma_f32_16x16x32_f16 v[12:15], v[128:131], v[228:231], v[12:15]
	v_mfma_f32_16x16x32_f16 v[100:103], v[180:183], v[228:231], v[100:103]
	v_mfma_f32_16x16x32_f16 v[36:39], v[152:155], v[208:211], v[36:39]
	v_mfma_f32_16x16x32_f16 v[44:47], v[184:187], v[208:211], v[44:47]
	v_mfma_f32_16x16x32_f16 v[20:23], v[152:155], v[216:219], v[20:23]
	v_mfma_f32_16x16x32_f16 v[32:35], v[184:187], v[216:219], v[32:35]
	v_mfma_f32_16x16x32_f16 v[4:7], v[152:155], v[224:227], v[4:7]
	v_mfma_f32_16x16x32_f16 v[108:111], v[184:187], v[224:227], v[108:111]
	v_mfma_f32_16x16x32_f16 v[12:15], v[152:155], v[232:235], v[12:15]
	v_mfma_f32_16x16x32_f16 v[100:103], v[184:187], v[232:235], v[100:103]
	v_mfma_f32_16x16x32_f16 v[40:43], v[188:191], v[204:207], v[40:43]
	v_mfma_f32_16x16x32_f16 v[28:31], v[196:199], v[204:207], v[28:31]
	v_mfma_f32_16x16x32_f16 v[24:27], v[188:191], v[212:215], v[24:27]
	v_mfma_f32_16x16x32_f16 v[16:19], v[196:199], v[212:215], v[16:19]
	v_mfma_f32_16x16x32_f16 v[104:107], v[188:191], v[220:223], v[104:107]
	v_mfma_f32_16x16x32_f16 v[0:3], v[196:199], v[220:223], v[0:3]
	v_mfma_f32_16x16x32_f16 v[96:99], v[188:191], v[228:231], v[96:99]
	v_mfma_f32_16x16x32_f16 v[8:11], v[196:199], v[228:231], v[8:11]
	v_mfma_f32_16x16x32_f16 v[40:43], v[192:195], v[208:211], v[40:43]
	v_mfma_f32_16x16x32_f16 v[28:31], v[200:203], v[208:211], v[28:31]
	v_mfma_f32_16x16x32_f16 v[24:27], v[192:195], v[216:219], v[24:27]
	v_mfma_f32_16x16x32_f16 v[16:19], v[200:203], v[216:219], v[16:19]
	v_mfma_f32_16x16x32_f16 v[104:107], v[192:195], v[224:227], v[104:107]
	v_mfma_f32_16x16x32_f16 v[0:3], v[200:203], v[224:227], v[0:3]
	v_mfma_f32_16x16x32_f16 v[96:99], v[192:195], v[232:235], v[96:99]
	v_mfma_f32_16x16x32_f16 v[8:11], v[200:203], v[232:235], v[8:11]
	s_barrier
	s_add_i32 s16, s16, 2
	s_add_u32 s14, s14, 0x100
	s_addc_u32 s15, s15, 0
	s_cmp_gt_u32 s16, 13
	s_mov_b64 s[0:1], s[4:5]

.LBB0_537:
	s_or_b64 exec, exec, s[0:1]
	s_and_b64 s[0:1], s[36:37], exec
	s_cselect_b32 s28, 16, 0x1000
	s_add_u32 s64, s76, 0x13d00000
	s_addc_u32 s65, s77, 0
	s_bfe_u32 s68, s96, 0x20006
	s_mul_i32 s0, s68, 0x3700
	s_add_i32 s71, s0, 0
	s_and_b32 s0, s96, 0xffffff00
	s_lshr_b32 s74, s96, 8
	s_add_i32 s84, s0, 0
	s_lshl_b32 s11, s74, 5
	s_add_i32 s80, s84, 0x12600
	s_cmpk_lt_u32 s96, 0x540
	v_readlane_b32 s20, v255, 31
	s_cselect_b64 s[40:41], -1, 0
	s_add_i32 s12, s20, -4
	s_lshl_b32 s13, s12, 2
	s_lshl_b32 s22, s12, 10
	s_cmpk_lt_u32 s96, 0x440
	s_cselect_b64 s[42:43], -1, 0
	s_lshl_b32 s66, s20, 10
	s_cmpk_lt_u32 s96, 0x340
	s_cselect_b64 s[46:47], -1, 0
	s_add_i32 s14, s20, 4
	s_lshl_b32 s15, s14, 2
	s_lshl_b32 s23, s14, 10
	s_cmpk_lt_u32 s96, 0x240
	s_cselect_b64 s[48:49], -1, 0
	s_add_i32 s16, s20, 8
	s_lshl_b32 s17, s16, 2
	s_lshl_b32 s24, s16, 10
	s_cmp_eq_u32 s20, 4
	s_cselect_b64 s[50:51], -1, 0
	s_cmp_eq_u32 s20, 2
	s_mov_b32 s0, 0xfc00000
	s_cselect_b32 s38, s0, 0x13d00000
	s_add_u32 s8, s76, s6
	s_addc_u32 s9, s77, 0
	s_mul_i32 s0, s20, 0x2400
	s_add_i32 s1, 0, 0x1a900
	s_add_i32 s81, s1, s0
	s_lshl_b32 s0, s74, 7
	s_add_i32 s83, s0, 0
	s_add_i32 s82, s81, 0x2000
	s_add_i32 s83, s83, 0x14800
	s_add_i32 s84, s84, 0x12400
	s_lshl_b32 s29, s20, 5
	s_add_u32 s6, s64, s6
	s_addc_u32 s7, s65, 0
	s_lshl_b32 s85, s33, 10
	s_add_u32 s18, s76, 0x10000
	v_writelane_b32 v255, s96, 33
	s_addc_u32 s19, s77, 0
	v_lshl_or_b32 v11, s68, 4, v9
	v_writelane_b32 v255, s18, 34
	v_add_u32_e32 v25, 1, v11
	v_lshlrev_b32_e32 v27, 3, v38
	v_writelane_b32 v255, s19, 35
	v_lshlrev_b32_e32 v10, 7, v25
	v_and_b32_e32 v22, 8, v27
	s_add_i32 s0, 0, 0x1cd00
	s_add_i32 s18, 0, 0x1f100
	v_add3_u32 v91, s1, v10, v22
	v_add3_u32 v92, s0, v10, v22
	v_add3_u32 v93, s18, v10, v22
	v_lshlrev_b32_e32 v10, 8, v25
	s_add_i32 s19, 0, 0x23900
	v_add3_u32 v28, s19, v10, v22
	v_lshlrev_b32_e32 v10, 7, v11
	v_add3_u32 v94, s1, v10, v22
	v_add3_u32 v95, s0, v10, v22
	v_add3_u32 v96, s18, v10, v22
	v_lshlrev_b32_e32 v10, 8, v11
	v_add3_u32 v29, s19, v10, v22
	v_add_u32_e32 v10, 1, v89
	s_add_i32 s19, 0, 0x21500
	v_lshl_add_u32 v32, v10, 7, s19
	v_xor_b32_e32 v10, v10, v39
	v_lshlrev_b32_e32 v10, 4, v10
	v_and_b32_e32 v33, 0x70, v10
	v_lshlrev_b32_e32 v10, 7, v89
	v_add_u32_e32 v34, s19, v10
	s_add_i32 s19, 0, 0x12800
	s_cmp_lg_u32 s12, 16
	v_add_u32_e32 v36, s19, v10
	v_or_b32_e32 v10, s13, v38
	s_cselect_b64 vcc, -1, 0
	v_xor_b32_e32 v22, v89, v39
	v_cndmask_b32_e32 v98, 64, v10, vcc
	v_bitop3_b32 v10, v38, v39, s13 bitop3:0x36
	v_lshlrev_b32_e32 v22, 4, v22
	v_and_or_b32 v10, v10, 7, v41
	v_and_b32_e32 v35, 0x70, v22
	v_lshlrev_b32_e32 v22, 4, v10
	v_mov_b32_e32 v10, 0
	v_mov_b32_e32 v23, v10
	s_cmp_lg_u32 s20, 16
	v_lshl_add_u64 v[48:49], s[4:5], 0, v[22:23]
	v_or_b32_e32 v22, s3, v38
	s_cselect_b64 vcc, -1, 0
	v_cndmask_b32_e32 v99, 64, v22, vcc
	v_bitop3_b32 v22, v38, v39, s3 bitop3:0x36
	v_and_or_b32 v22, v22, 7, v41
	v_lshlrev_b32_e32 v22, 4, v22
	s_cmp_lg_u32 s14, 16
	v_lshl_add_u64 v[50:51], s[4:5], 0, v[22:23]
	v_or_b32_e32 v22, s15, v38
	s_cselect_b64 vcc, -1, 0
	v_cndmask_b32_e32 v100, 64, v22, vcc
	v_bitop3_b32 v22, v38, v39, s15 bitop3:0x36
	v_and_or_b32 v22, v22, 7, v41
	v_lshlrev_b32_e32 v22, 4, v22
	s_cmp_lg_u32 s16, 16
	v_lshl_add_u64 v[52:53], s[4:5], 0, v[22:23]
	v_or_b32_e32 v22, s17, v38
	s_cselect_b64 vcc, -1, 0
	v_cndmask_b32_e32 v101, 64, v22, vcc
	v_bitop3_b32 v22, v38, v39, s17 bitop3:0x36
	v_and_or_b32 v22, v22, 7, v41
	v_lshlrev_b32_e32 v22, 4, v22
	v_lshl_add_u64 v[54:55], s[4:5], 0, v[22:23]
	v_xor_b32_e32 v22, v38, v20
	s_movk_i32 s10, 0x3700
	v_or_b32_e32 v22, v22, v41
	v_lshlrev_b32_e32 v41, 5, v9
	v_lshrrev_b32_e32 v45, 7, v42
	v_cmp_gt_u32_e64 s[0:1], 16, v40
	v_or_b32_e32 v103, v27, v41
	v_lshl_add_u32 v104, v40, 2, s71
	v_add_u32_e32 v40, s71, v41
	v_lshrrev_b32_e32 v41, 2, v9
	v_mul_lo_u32 v45, v45, s10
	v_or_b32_e32 v41, v90, v41
	v_add_u32_e32 v67, 0, v45
	v_bfe_u32 v45, v42, 3, 4
	v_mul_u32_u24_e32 v41, 0x48, v41
	v_and_b32_e32 v21, 12, v21
	v_mul_u32_u24_e32 v45, 0x48, v45
	v_or_b32_e32 v24, s11, v90
	v_add_lshl_u32 v105, v21, v41, 1
	v_lshl_or_b32 v21, v89, 6, v8
	v_add_lshl_u32 v8, v45, v8, 1
	v_mov_b32_e32 v45, v10
	v_and_b32_e32 v26, 7, v25
	v_lshl_add_u64 v[60:61], s[6:7], 0, v[44:45]
	v_cmp_eq_u32_e64 s[6:7], 0, v42
	v_lshrrev_b32_e32 v42, 3, v24
	v_and_b32_e32 v62, 8, v42
	v_bitop3_b32 v63, v42, v26, 5 bitop3:0x6c
	v_or_b32_e32 v63, v63, v62
	v_lshlrev_b32_e32 v68, 4, v63
	v_add_u32_e32 v63, 64, v24
	v_bitop3_b32 v45, v42, v25, 7 bitop3:0x78
	v_lshrrev_b32_e32 v64, 3, v63
	v_xor_b32_e32 v69, v42, v20
	v_bitop3_b32 v42, v42, v20, 5 bitop3:0x6c
	v_and_b32_e32 v65, 8, v64
	v_or_b32_e32 v42, v42, v62
	v_bitop3_b32 v62, v64, v20, 5 bitop3:0x6c
	v_or_b32_e32 v62, v62, v65
	v_lshlrev_b32_e32 v108, 4, v69
	v_lshlrev_b32_e32 v69, 4, v62
	v_or_b32_e32 v62, 16, v24
	v_lshlrev_b32_e32 v22, 4, v22
	v_lshlrev_b32_e32 v71, 1, v63
	v_lshrrev_b32_e32 v63, 3, v62
	v_lshl_add_u64 v[56:57], s[4:5], 0, v[22:23]
	v_xor_b32_e32 v22, v88, v20
	v_bitop3_b32 v26, v64, v26, 5 bitop3:0x6c
	v_bitop3_b32 v64, v63, v25, 7 bitop3:0x78
	v_lshlrev_b32_e32 v22, 4, v22
	v_or_b32_e32 v26, v26, v65
	v_lshlrev_b32_e32 v111, 4, v64
	v_and_b32_e32 v64, 8, v63
	v_bitop3_b32 v65, v63, v25, 7 bitop3:0x28
	s_movk_i32 s18, 0x48
	v_lshl_add_u64 v[58:59], s[8:9], 0, v[22:23]
	v_or_b32_e32 v23, s11, v9
	v_or_b32_e32 v65, v65, v64
	v_mul_u32_u24_e32 v30, 0x48, v11
	v_mul_u32_u24_e32 v31, 0x48, v9
	v_lshlrev_b32_e32 v97, 2, v11
	v_or_b32_e32 v22, 16, v90
	v_lshlrev_b32_e32 v72, 4, v65
	v_add_u32_e32 v65, 0x50, v24
	v_mul_lo_u32 v23, v23, s18
	v_mad_u32_u24 v11, v11, s18, 32
	v_lshlrev_b32_e32 v70, 1, v24
	v_add_lshl_u32 v109, v24, v30, 1
	v_add_lshl_u32 v110, v24, v31, 1
	v_lshrrev_b32_e32 v73, 3, v65
	v_xor_b32_e32 v75, v63, v20
	v_bitop3_b32 v63, v63, v20, 7 bitop3:0x6c
	v_add_lshl_u32 v113, v62, v30, 1
	v_add_lshl_u32 v115, v30, v90, 1
	v_add_lshl_u32 v116, v22, v30, 1
	v_add_u32_e32 v30, 0x480, v23
	v_add_lshl_u32 v119, v11, v90, 1
	v_add_lshl_u32 v120, v11, v22, 1
	v_or_b32_e32 v11, 32, v90
	v_lshlrev_b32_e32 v123, 2, v24
	v_or_b32_e32 v24, 1, v90
	v_cmp_eq_u32_e32 vcc, v90, v9
	v_lshlrev_b32_e32 v106, 5, v20
	v_and_b32_e32 v74, 8, v73
	v_bitop3_b32 v25, v73, v25, 7 bitop3:0x28
	v_or_b32_e32 v63, v63, v64
	v_bitop3_b32 v20, v73, v20, 7 bitop3:0x6c
	v_lshlrev_b32_e32 v73, 1, v62
	v_add_lshl_u32 v114, v62, v31, 1
	v_add_lshl_u32 v118, v30, v90, 1
	v_add_lshl_u32 v122, v11, v30, 1
	v_lshlrev_b32_e32 v124, 2, v62
	v_or_b32_e32 v30, 2, v90
	v_cndmask_b32_e64 v62, 0, 1.0, vcc
	v_cmp_eq_u32_e32 vcc, v24, v9
	v_lshlrev_b32_e32 v112, 4, v75
	v_lshlrev_b32_e32 v75, 4, v63
	v_add_lshl_u32 v117, v90, v23, 1
	v_add_lshl_u32 v121, v11, v23, 1
	v_add_lshl_u32 v125, v90, v31, 1
	v_add_lshl_u32 v23, v11, v31, 1
	v_or_b32_e32 v31, 3, v90
	v_cndmask_b32_e64 v63, 0, 1.0, vcc
	v_cmp_eq_u32_e32 vcc, v30, v9
	v_cmp_eq_u32_e64 s[4:5], 0, v9
	v_mad_u32_u24 v37, v9, s18, 16
	v_cmp_lt_u32_e64 s[8:9], v90, v9
	v_cmp_gt_u32_e64 s[10:11], v90, v9
	v_cmp_lt_u32_e64 s[12:13], v24, v9
	v_cmp_lt_u32_e64 s[14:15], v30, v9
	v_cmp_gt_u32_e64 s[16:17], v30, v9
	v_cmp_lt_u32_e64 s[18:19], v31, v9
	v_cmp_gt_u32_e64 s[20:21], v31, v9
	v_cndmask_b32_e64 v64, 0, 1.0, vcc
	v_cmp_eq_u32_e32 vcc, v31, v9
	v_lshlrev_b32_e32 v9, 2, v9
	v_lshl_add_u32 v24, v38, 10, s97
	s_mov_b32 s3, 0xdc00
	v_add3_u32 v126, v24, v9, s3
	v_and_b32_e32 v9, 3, v39
	s_movk_i32 s25, 0x2400
	v_lshlrev_b32_e32 v43, 2, v21
	v_lshlrev_b32_e32 v21, 1, v21
	v_lshl_or_b32 v9, v9, 3, s29
	v_lshlrev_b32_e32 v24, 1, v41
	s_waitcnt lgkmcnt(0)
	s_barrier
	v_lshlrev_b32_e32 v66, 2, v89
	v_or_b32_e32 v25, v25, v74
	v_or_b32_e32 v20, v20, v74
	v_add3_u32 v128, v9, v24, s25
	v_mov_b32_e32 v9, 0x3540
	v_add_u32_e32 v151, v67, v8
	v_add_u32_e32 v8, 0, v21
	s_mov_b32 s39, 0
	v_and_b32_e32 v102, 48, v39
	v_lshlrev_b32_e32 v26, 4, v26
	v_lshlrev_b32_e32 v42, 4, v42
	v_lshlrev_b32_e32 v25, 4, v25
	v_lshlrev_b32_e32 v20, 4, v20
	v_lshlrev_b32_e32 v74, 1, v65
	v_add_lshl_u32 v22, v37, v90, 1
	v_add_lshl_u32 v11, v11, v37, 1
	v_writelane_b32 v255, s97, 32
	v_lshl_or_b32 v129, v38, 4, v9
	s_add_i32 s3, 0, 0x15c00
	s_add_i32 s88, s22, 0
	s_add_i32 s89, s23, 0
	s_add_i32 s90, s24, 0
	v_add_u32_e32 v9, 0, v66
	v_add_u32_e32 v152, 0x12800, v8
	v_mbcnt_lo_u32_b32 v8, -1, 0
	s_mov_b64 s[52:53], s[38:39]
	v_add_u32_e32 v107, s70, v89
	v_lshlrev_b32_e32 v45, 4, v45
	v_cndmask_b32_e64 v65, 0, 1.0, vcc
	v_add_u32_e32 v127, 0x2d00, v103
	v_writelane_b32 v255, s29, 44
	v_or_b32_e32 v130, 0x3500, v102
	v_add_u32_e32 v131, v28, v68
	v_add_u32_e32 v132, v28, v26
	v_add_u32_e32 v133, v29, v42
	v_add_u32_e32 v134, v29, v69
	v_add_u32_e32 v135, s3, v70
	v_add_u32_e32 v136, s3, v71
	s_mov_b32 s86, 0x4038aa3b
	s_add_i32 s67, 0, 0x10000
	v_add_u32_e32 v137, v28, v72
	v_add_u32_e32 v138, v28, v25
	v_add_u32_e32 v139, v29, v75
	v_add_u32_e32 v140, v29, v20
	v_add_u32_e32 v141, s3, v73
	v_add_u32_e32 v142, s3, v74
	v_add_u32_e32 v143, v32, v33
	v_add_u32_e32 v145, v34, v35
	s_mov_b32 s87, 0xbfb8aa3b
	v_add_u32_e32 v146, v36, v44
	s_add_i32 s88, s88, 0x23900
	s_add_i32 s89, s89, 0x23900
	s_add_i32 s90, s90, 0x23900
	s_add_i32 s91, 0, 0x27900
	s_add_i32 s92, s81, 0x400
	s_add_i32 s93, s81, 0x800
	s_add_i32 s94, s81, 0xc00
	s_add_i32 s95, s81, 0x1400
	s_add_i32 s96, s81, 0x1800
	s_add_i32 s97, s81, 0x1c00
	s_add_i32 s3, 0, 0x16100
	s_add_i32 s69, 0, 0x18500
	v_mov_b32_e32 v147, 0xbf92477c
	v_add_u32_e32 v148, v40, v27
	s_xor_b64 s[54:55], s[26:27], -1
	v_add_u32_e32 v149, 0, v43
	v_add_u32_e32 v150, 0x12400, v9
	v_mov_b32_e32 v153, 0x3a27c5ac
	v_mbcnt_hi_u32_b32 v144, -1, v8
	v_add_u32_e32 v154, s71, v22
	v_add_u32_e32 v155, s71, v23
	v_add_u32_e32 v156, s71, v11
	s_mov_b32 s33, s28
	s_mov_b32 s29, 0
	v_add_u32_e32 v220, v91, v111
	v_add_u32_e32 v231, s3, v118
	v_add_u32_e32 v209, v95, v108
	v_add_u32_e32 v213, s67, v109
	v_xor_b32_e32 v242, 16, v144
	v_and_b32_e32 v241, 64, v144
	v_add_u32_e32 v21, 64, v241
	v_cmp_lt_i32_e32 vcc, v242, v21
	s_nop 1
	v_cndmask_b32_e32 v20, v144, v242, vcc
	v_lshlrev_b32_e32 v221, 2, v20
	v_add_u32_e32 v218, v96, v112
	v_add_u32_e32 v239, 0x12600, v97
	v_add_u32_e32 v225, 0x15d80, v44
	v_add_u32_e32 v233, s67, v119
	v_add_u32_e32 v238, s69, v122
	v_add_u32_e32 v207, v92, v45
	v_add_u32_e32 v224, s71, v114
	v_add_u32_e32 v208, v94, v108
	v_add_u32_e32 v232, s69, v118
	v_add_u32_e32 v211, v93, v45
	v_add_u32_e32 v216, v94, v112
	v_add_u32_e32 v210, v96, v108
	v_add_u32_e32 v219, v93, v111
	v_add_u32_e32 v226, s83, v102
	v_add_u32_e32 v227, s67, v115
	v_add_u32_e32 v223, s67, v113
	v_or_b32_e32 v240, v102, v241
	v_add_u32_e32 v237, s3, v122
	v_add_u32_e32 v234, s67, v120
	v_add_u32_e32 v235, s3, v121
	v_xor_b32_e32 v243, 32, v144
	v_add_u32_e32 v236, s69, v121
	v_add_u32_e32 v230, s69, v117
	v_add_u32_e32 v212, v91, v45
	v_add_u32_e32 v229, s3, v117
	v_add_u32_e32 v214, s71, v110
	v_add_u32_e32 v228, s67, v116
	v_add_u32_e32 v215, v92, v111
	v_add_u32_e32 v217, v95, v112
	v_cmp_lt_i32_e32 vcc, v243, v21
	s_nop 1
	v_cndmask_b32_e32 v22, v144, v243, vcc
	v_lshlrev_b32_e32 v222, 2, v22
	v_mov_b32_e32 v252, 0
	s_waitcnt vmcnt(0)
